# static s_setprio 1 for waves 4-7 during mLSTM and attention phases (reset to 0 at phase exit)
# speedup vs baseline: 1.0043x; 1.0043x over previous
; __device__ __forceinline__ void p2_mlstm(const Params& p, LAS unsigned char* lds) {
;     const int tid = threadIdx.x, wid = __builtin_amdgcn_readfirstlane(tid >> 6), lane = tid & 63, r = lane & 15, q = lane >> 4;
;     unsigned char* ws = p.ws;
;     const bf16_t* R1 = (const bf16_t*)(ws + WS_R1); const bf16_t* QK = (const bf16_t*)(ws + WS_R2);
;     const float* GATES = (const float*)(ws + WS_GATES);
;     float* SSQ = (float*)(ws + WS_SSQ);
;     bf16_t* HM = (bf16_t*)((unsigned char*)p.out + OUT_HM);
;     LAS unsigned char* KB = lds + ML_KB; LAS unsigned char* VT = lds + ML_VT; LAS unsigned char* CT = lds + ML_CT; LAS unsigned char* WVT = lds + ML_WVT;
;     LAS unsigned char* NV = lds + 149760;
;     LAS unsigned char* WV = lds + 150272;
;     LAS float* PU = (LAS float*)(lds + ML_G); LAS float* PCM = PU + 2048; LAS float* PB = PU + 4096; LAS float* PBT = PU + 6144; LAS float* PCT = PBT + 16; LAS float* MPREV = PBT + 32; LAS float* MM127 = PBT + 48;
;     for (int it = blockIdx.x; it < 256; it += gridDim.x) {
;         const int xcd = it & 7, idx = it >> 3; const int bh = xcd * 4 + (idx >> 3), sl = idx & 7; const int b = bh >> 2, h = bh & 3;
;         const int tokbase = b * SEQ;
;         f32x4 cacc[3][2];
; #pragma unroll
;         for (int vt = 0; vt < 3; ++vt)
; #pragma unroll
;             for (int dd = 0; dd < 2; ++dd) cacc[vt][dd] = (f32x4){0.f, 0.f, 0.f, 0.f};
;         for (int i = tid; i < (ML_G - ML_VT) / 4; i += 512) ((LAS unsigned*)(lds + ML_VT))[i] = 0u;
; #pragma unroll 1
;         for (int cc = 0; cc < 2; ++cc) {
;             const int ck = 2 * wid + cc; const int t0 = tokbase + ck * 128 + 2 * lane;
;             const float ig0 = GATES[(size_t)t0 * 8 + h], lf0 = GATES[(size_t)t0 * 8 + 4 + h], ig1 = GATES[(size_t)(t0 + 1) * 8 + h], lf1 = GATES[(size_t)(t0 + 1) * 8 + 4 + h];
;             float sc = lf0 + lf1;
; #pragma unroll
;             for (int off = 1; off < 64; off <<= 1) { const float t = __shfl_up(sc, off); if (lane >= off) sc += t; }
;             const float b1 = sc, b0 = sc - lf1;
;             const float u0 = ig0 - b0, u1 = ig1 - b1;
;             float cm = fmaxf(u0, u1);
; #pragma unroll
;             for (int off = 1; off < 64; off <<= 1) { const float t = __shfl_up(cm, off); if (lane >= off) cm = fmaxf(cm, t); }
;             float cprev = __shfl_up(cm, 1); if (lane == 0) cprev = -1e30f;
.LBB0_233:
	s_cmp_lt_i32 s90, 4
	s_cselect_b64 s[0:1], -1, 0
	s_add_u32 s4, s74, 0x2000000
	s_addc_u32 s5, s75, 0
	v_writelane_b32 v254, s4, 23
	s_and_b64 s[0:1], s[0:1], s[2:3]
	s_nop 0
	v_writelane_b32 v254, s5, 24
	v_writelane_b32 v254, s0, 25
	s_andn2_b64 vcc, exec, s[0:1]
	s_nop 0
	v_writelane_b32 v254, s1, 26
	s_cbranch_vccnz .LBB0_359
	s_cmpk_gt_i32 s84, 0xff
	v_readfirstlane_b32 s0, v212
	s_cbranch_scc1 .LBB0_359
	s_cmp_ge_u32 s0, 0x100
	s_cbranch_scc0 .Lprio3_done
	s_setprio 1
.Lprio3_done:
	v_writelane_b32 v254, s92, 27
	s_add_u32 s1, s88, 0x1d00000
	v_and_b32_e32 v4, 15, v212
	v_writelane_b32 v254, s93, 28
	v_writelane_b32 v254, s68, 29
	v_bfe_u32 v0, v212, 4, 2
	v_lshlrev_b32_e32 v7, 3, v0
	v_writelane_b32 v254, s69, 30
	v_writelane_b32 v254, s70, 31
	v_writelane_b32 v254, s71, 32
	v_writelane_b32 v254, s72, 33
	v_writelane_b32 v254, s73, 34
	v_writelane_b32 v254, s74, 35
	v_writelane_b32 v254, s75, 36
	v_writelane_b32 v254, s1, 37
	s_addc_u32 s1, s89, 0
	v_writelane_b32 v254, s1, 39
	s_add_u32 s1, s88, 0xfd80000
	v_writelane_b32 v254, s1, 41
	v_writelane_b32 v254, s88, 43
	s_addc_u32 s1, s89, 0
	v_lshlrev_b32_e32 v195, 2, v0
	v_writelane_b32 v254, s89, 44
	v_writelane_b32 v254, s90, 45
	s_add_i32 s33, 0, 0x10800
	v_bfe_u32 v15, v212, 2, 2
	v_mul_u32_u24_e32 v16, 0x210, v4
	v_and_b32_e32 v197, 48, v212
	v_writelane_b32 v254, s91, 46
	v_lshrrev_b32_e32 v8, 2, v212
	s_movk_i32 s35, 0x70
	v_mov_b32_e32 v10, s33
	s_add_i32 s36, 0, 0x14000
	v_or_b32_e32 v17, v195, v15
	v_or_b32_e32 v15, v7, v15
	v_mov_b32_e32 v23, 0x1c00
	v_add3_u32 v198, 0, v16, v197
	v_or_b32_e32 v16, 2, v195
	v_writelane_b32 v254, s1, 47
	s_movk_i32 s1, 0x80
	v_mad_u32_u24 v11, v8, s35, v10
	v_mov_b32_e32 v13, s36
	s_add_i32 s38, 0, 0x17800
	v_mad_u32_u24 v23, v15, s35, v23
	v_cmp_gt_u32_e64 s[28:29], v16, v4
	v_or_b32_e32 v16, 3, v195
	v_mad_u32_u24 v10, v17, s35, v10
	v_or_b32_e32 v17, 32, v15
	v_cmp_gt_u32_e64 s[6:7], s1, v212
	v_lshlrev_b32_e32 v6, 2, v212
	s_add_i32 s1, 0, 0x24900
	v_mad_u32_u24 v14, v8, s35, v13
	s_movk_i32 s37, 0x210
	v_mov_b32_e32 v22, s38
	v_cmp_gt_u32_e64 s[30:31], v16, v4
	v_mad_u32_u24 v16, v15, s35, v13
	v_mad_u32_u24 v199, v17, s35, v13
	v_add_u32_e32 v13, s36, v23
	v_or_b32_e32 v17, 0x60, v15
	v_lshlrev_b32_e32 v25, 1, v4
	s_add_i32 s36, 0, 0x24920
	v_add_u32_e32 v192, s1, v6
	v_mad_u32_u24 v22, v15, s35, v22
	v_add_u32_e32 v26, s36, v25
	v_add_u32_e32 v25, s1, v25
	v_mad_u32_u24 v200, v17, s37, 0
	v_mad_u32_u24 v15, v15, s37, 0
	s_lshr_b32 s1, s0, 6
	s_lshr_b32 s37, s0, 5
	s_lshl_b32 s36, s1, 1
	s_and_b32 s37, s37, 0x7fffffc
	s_and_b32 s78, s0, 0xffffffc0
	s_cmp_lg_u32 s37, 0
	v_add_u32_e32 v24, s38, v23
	v_add_u32_e32 v27, s38, v7
	s_cselect_b64 s[38:39], -1, 0
	s_cmp_gt_u32 s0, 63
	s_cselect_b64 s[88:89], -1, 0
	s_cmpk_gt_u32 s0, 0x7f
	v_mbcnt_lo_u32_b32 v29, -1, 0
	s_cselect_b64 s[90:91], -1, 0
	s_cmpk_lt_u32 s0, 0x80
	v_mbcnt_hi_u32_b32 v29, -1, v29
	s_cselect_b64 s[96:97], -1, 0
	s_cmp_eq_u32 s1, 1
	v_and_b32_e32 v30, 64, v29
	v_add_u32_e32 v31, -1, v29
	s_cselect_b64 s[76:77], -1, 0
	s_cmpk_gt_u32 s0, 0xff
	v_cmp_lt_i32_e32 vcc, v31, v30
	s_cselect_b64 s[66:67], -1, 0
	s_cmpk_lt_u32 s0, 0x100
	v_cndmask_b32_e32 v31, v31, v29, vcc
	s_cselect_b64 s[86:87], -1, 0
	s_cmpk_lt_u32 s0, 0xc0
	v_lshlrev_b32_e32 v201, 2, v31
	v_or_b32_e32 v31, v30, v4
	s_cselect_b64 s[46:47], -1, 0
	s_cmp_eq_u32 s1, 3
	v_lshlrev_b32_e32 v204, 2, v31
	v_xor_b32_e32 v31, 16, v29
	v_add_u32_e32 v32, 64, v30
	s_cselect_b64 s[92:93], -1, 0
	s_cmp_gt_u32 s37, 5
	v_cmp_lt_i32_e32 vcc, v31, v32
	s_cselect_b64 s[56:57], -1, 0
	s_cmp_gt_u32 s37, 6
	v_cndmask_b32_e32 v31, v29, v31, vcc
	s_cselect_b64 s[58:59], -1, 0
	s_cmpk_gt_u32 s0, 0x17f
	v_lshlrev_b32_e32 v205, 2, v31
	v_xor_b32_e32 v31, 32, v29
	s_cselect_b64 s[60:61], -1, 0
	s_cmpk_lt_u32 s0, 0x180
	v_cmp_lt_i32_e32 vcc, v31, v32
	v_add_u32_e32 v32, -2, v29
	s_cselect_b64 s[48:49], -1, 0
	s_cmpk_lt_u32 s0, 0x140
	v_cndmask_b32_e32 v31, v29, v31, vcc
	v_cmp_lt_i32_e32 vcc, v32, v30
	s_cselect_b64 s[72:73], -1, 0
	s_cmp_eq_u32 s1, 5
	v_cndmask_b32_e32 v32, v32, v29, vcc
	s_cselect_b64 s[74:75], -1, 0
	s_cmp_gt_u32 s37, 9
	v_lshlrev_b32_e32 v208, 2, v32
	v_add_u32_e32 v32, -4, v29
	s_cselect_b64 s[68:69], -1, 0
	s_cmp_gt_u32 s37, 10
; __device__ __forceinline__ void p2_mlstm(const Params& p, LAS unsigned char* lds) {
;     const int tid = threadIdx.x, wid = __builtin_amdgcn_readfirstlane(tid >> 6), lane = tid & 63, r = lane & 15, q = lane >> 4;
;     unsigned char* ws = p.ws;
;     const bf16_t* R1 = (const bf16_t*)(ws + WS_R1); const bf16_t* QK = (const bf16_t*)(ws + WS_R2);
;     const float* GATES = (const float*)(ws + WS_GATES);
;     float* SSQ = (float*)(ws + WS_SSQ);
;     bf16_t* HM = (bf16_t*)((unsigned char*)p.out + OUT_HM);
;     LAS unsigned char* KB = lds + ML_KB; LAS unsigned char* VT = lds + ML_VT; LAS unsigned char* CT = lds + ML_CT; LAS unsigned char* WVT = lds + ML_WVT;
;     LAS unsigned char* NV = lds + 149760;
;     LAS unsigned char* WV = lds + 150272;
;     LAS float* PU = (LAS float*)(lds + ML_G); LAS float* PCM = PU + 2048; LAS float* PB = PU + 4096; LAS float* PBT = PU + 6144; LAS float* PCT = PBT + 16; LAS float* MPREV = PBT + 32; LAS float* MM127 = PBT + 48;
;     for (int it = blockIdx.x; it < 256; it += gridDim.x) {
;         const int xcd = it & 7, idx = it >> 3; const int bh = xcd * 4 + (idx >> 3), sl = idx & 7; const int b = bh >> 2, h = bh & 3;
;         const int tokbase = b * SEQ;
;         f32x4 cacc[3][2];
; #pragma unroll
;         for (int vt = 0; vt < 3; ++vt)
; #pragma unroll
;             for (int dd = 0; dd < 2; ++dd) cacc[vt][dd] = (f32x4){0.f, 0.f, 0.f, 0.f};
;         for (int i = tid; i < (ML_G - ML_VT) / 4; i += 512) ((LAS unsigned*)(lds + ML_VT))[i] = 0u;
; #pragma unroll 1
;         for (int cc = 0; cc < 2; ++cc) {
;             const int ck = 2 * wid + cc; const int t0 = tokbase + ck * 128 + 2 * lane;
;             const float ig0 = GATES[(size_t)t0 * 8 + h], lf0 = GATES[(size_t)t0 * 8 + 4 + h], ig1 = GATES[(size_t)(t0 + 1) * 8 + h], lf1 = GATES[(size_t)(t0 + 1) * 8 + 4 + h];
;             float sc = lf0 + lf1;
; #pragma unroll
;             for (int off = 1; off < 64; off <<= 1) { const float t = __shfl_up(sc, off); if (lane >= off) sc += t; }
;             const float b1 = sc, b0 = sc - lf1;
;             const float u0 = ig0 - b0, u1 = ig1 - b1;
;             float cm = fmaxf(u0, u1);
; #pragma unroll
;             for (int off = 1; off < 64; off <<= 1) { const float t = __shfl_up(cm, off); if (lane >= off) cm = fmaxf(cm, t); }
;             float cprev = __shfl_up(cm, 1); if (lane == 0) cprev = -1e30f;
	v_writelane_b32 v254, s6, 49
	v_cmp_lt_i32_e32 vcc, v32, v30
	s_cselect_b64 s[70:71], -1, 0
	s_cmpk_lt_u32 s0, 0x1c0
	v_writelane_b32 v254, s7, 50
	v_cndmask_b32_e32 v32, v32, v29, vcc
	s_cselect_b64 s[54:55], -1, 0
	s_cmpk_lt_u32 s0, 0x200
	v_lshlrev_b32_e32 v209, 2, v32
	v_add_u32_e32 v32, -8, v29
	s_cselect_b64 s[62:63], -1, 0
	s_cmp_eq_u32 s1, 7
	v_writelane_b32 v254, s82, 51
	v_cmp_lt_i32_e32 vcc, v32, v30
	s_cselect_b64 s[64:65], -1, 0
	v_writelane_b32 v254, s83, 52
	s_lshl_b32 s0, s82, 2
	v_cndmask_b32_e32 v32, v32, v29, vcc
	v_add_u32_e32 v215, s33, v6
	v_writelane_b32 v254, s0, 53
	v_lshlrev_b32_e32 v6, 11, v4
	s_mul_i32 s0, s1, 0x14000
	s_movk_i32 s34, 0x1400
	v_lshlrev_b32_e32 v210, 2, v32
	v_add_u32_e32 v32, -16, v29
	v_lshl_or_b32 v217, s1, 15, v6
	v_mov_b32_e32 v6, s0
	v_and_b32_e32 v5, 63, v212
	v_cmp_lt_i32_e32 vcc, v32, v30
	v_mad_u32_u24 v6, v4, s34, v6
	v_cmp_eq_u32_e64 s[4:5], 63, v5
	v_cndmask_b32_e32 v32, v32, v29, vcc
	v_or_b32_e32 v6, v6, v195
	s_mul_i32 s0, s1, 0x28000
	v_writelane_b32 v254, s84, 54
	v_lshlrev_b32_e32 v2, 3, v212
	v_lshlrev_b32_e32 v0, 4, v212
	v_lshl_or_b32 v202, s1, 4, v4
	v_lshlrev_b32_e32 v206, 2, v31
	v_lshl_or_b32 v31, s1, 5, v4
	v_lshlrev_b32_e32 v211, 2, v32
	v_subrev_u32_e32 v32, 32, v29
	v_add_u32_e32 v218, 0xc00, v6
	s_movk_i32 s1, 0x2800
	v_mov_b32_e32 v6, s0
	v_writelane_b32 v254, s4, 55
	v_lshlrev_b32_e32 v191, 1, v5
	v_cmp_eq_u32_e64 s[2:3], 0, v5
	v_lshlrev_b32_e32 v1, 6, v212
	v_and_b32_e32 v3, 0xf8, v2
	s_mov_b32 s8, 0xf800
	v_and_b32_e32 v0, 0x1f0, v0
	v_cmp_eq_u32_e64 s[10:11], 0, v4
	v_cmp_gt_u32_e64 s[12:13], 16, v5
	v_cmp_lt_u32_e64 s[14:15], 15, v5
	v_cmp_gt_u32_e64 s[16:17], 2, v5
	v_cmp_gt_u32_e64 s[18:19], 4, v5
	v_cmp_gt_u32_e64 s[20:21], 8, v5
	v_cmp_gt_u32_e64 s[22:23], 32, v5
	v_lshrrev_b32_e32 v5, 5, v212
	v_add_u32_e32 v18, 0x200, v212
	v_add_u32_e32 v19, 0x600, v212
	v_add_u32_e32 v20, 0xa00, v212
	v_add_u32_e32 v21, 0xe00, v212
	v_cmp_gt_u32_e64 s[24:25], v195, v4
	v_cmp_lt_u32_e64 s[26:27], v195, v4
	v_cmp_lt_i32_e32 vcc, v32, v30
	v_lshl_or_b32 v216, v4, 2, s78
	v_mad_u32_u24 v4, v4, s1, v6
	v_writelane_b32 v254, s5, 56
	v_and_or_b32 v193, v1, s8, v3
	v_mul_u32_u24_e32 v1, 0x1400, v8
	v_and_b32_e32 v3, 3, v212
	v_add_u32_e32 v9, 0, v0
	v_and_b32_e32 v196, 24, v2
	v_mov_b32_e32 v0, 0x3f803f80
	v_lshlrev_b32_e32 v8, 1, v8
	v_mul_u32_u24_e32 v5, 0x210, v5
	v_lshrrev_b32_e32 v18, 5, v18
	v_lshrrev_b32_e32 v19, 5, v19
	v_lshrrev_b32_e32 v20, 5, v20
	v_lshrrev_b32_e32 v21, 5, v21
	v_cndmask_b32_e32 v29, v32, v29, vcc
	v_or_b32_e32 v4, v4, v7
	v_writelane_b32 v254, s62, 57
	v_lshl_or_b32 v1, v3, 3, v1
	v_lshlrev_b32_e32 v12, 4, v3
	v_cndmask_b32_e64 v0, 0, v0, s[10:11]
	v_mul_u32_u24_e32 v18, 0x210, v18
	v_mul_u32_u24_e32 v19, 0x210, v19
	v_mul_u32_u24_e32 v20, 0x210, v20
	v_mul_u32_u24_e32 v21, 0x210, v21
	v_add_u32_e32 v23, 0x1c00, v199
	v_add_u32_e32 v17, 0xffffbe00, v200
	v_add_u32_e32 v28, 0xffff7c00, v200
	v_or_b32_e32 v207, s78, v196
	v_lshlrev_b32_e32 v213, 2, v29
	v_mul_lo_u32 v29, v31, s35
	v_add_u32_e32 v219, 0x2000, v4
	v_add_u32_e32 v220, 0x2020, v4
	v_and_b32_e32 v4, 0x3fc, v212
	v_add_u32_e32 v222, v9, v5
	v_add_u32_e32 v5, 0, v8
	v_writelane_b32 v254, s63, 58
	v_add_u32_e32 v194, 0x800, v1
	v_cmp_eq_u32_e64 s[8:9], 0, v3
	v_mov_b32_e32 v1, v0
	v_mov_b32_e32 v2, v0
	v_mov_b32_e32 v3, v0
	v_lshl_or_b32 v203, v202, 11, v7
	v_add_u32_e32 v214, 0xfffffe00, v212
	s_lshl_b32 s33, s84, 2
	v_or_b32_e32 v221, 0x1e800, v4
	v_mov_b32_e32 v4, 0
	s_mov_b32 s37, 0x30000
	v_add_u32_e32 v223, v9, v18
	v_add_u32_e32 v224, v9, v19
	v_add_u32_e32 v225, v9, v20
	v_add_u32_e32 v226, v9, v21
	v_add_u32_e32 v227, v11, v12
	v_add_u32_e32 v228, v14, v12
	v_add_u32_e32 v229, 0x24b00, v5
	v_add_u32_e32 v230, v24, v196
	v_add_u32_e32 v231, v15, v207
	v_add_u32_e32 v232, v16, v196
	v_add_u32_e32 v233, v28, v207
	v_add_u32_e32 v234, v17, v207
	v_add_u32_e32 v235, v13, v196
	v_add_u32_e32 v236, v23, v196
	v_add_u32_e32 v237, v27, v29
	v_add_u32_e32 v238, s78, v25
	v_add_u32_e32 v239, s78, v26
	v_mov_b32_e32 v240, 0xf149f2ca
	v_add_u32_e32 v241, v22, v196
	v_add_u32_e32 v242, v10, v196
	v_mov_b32_e32 v243, 0x2800
	v_writelane_b32 v254, s64, 59
	s_nop 1
	v_writelane_b32 v254, s65, 60
	s_branch .LBB0_237

; __device__ __forceinline__ void p2_mlstm(const Params& p, LAS unsigned char* lds) {
;     ...
;         __syncthreads();
;     }
; }
.LBB0_358:
	s_setprio 0
	v_readlane_b32 s68, v254, 29
	v_readlane_b32 s82, v254, 51
	v_readlane_b32 s88, v254, 43
	v_readlane_b32 s92, v254, 27
	v_readlane_b32 s72, v254, 33
	v_readlane_b32 s73, v254, 34
	v_readlane_b32 s74, v254, 35
	v_readlane_b32 s75, v254, 36
	v_readlane_b32 s84, v254, 54
	v_readlane_b32 s83, v254, 52
	v_readlane_b32 s89, v254, 44
	v_readlane_b32 s90, v254, 45
	v_readlane_b32 s91, v254, 46
	v_readlane_b32 s93, v254, 28
	v_readlane_b32 s69, v254, 30
	v_readlane_b32 s70, v254, 31
	v_readlane_b32 s71, v254, 32

; #define LAS __attribute__((address_space(3)))
; __device__ __forceinline__ void p4_attn(const Params& p, LAS unsigned char* lds, const int dummy) {
;     const int tid = threadIdx.x, wid = __builtin_amdgcn_readfirstlane(tid >> 6), lane = tid & 63, r = lane & 15, q = lane >> 4;
;     unsigned char* ws = p.ws;
;     bf16_t* R1 = (bf16_t*)(ws + WS_R1);
;     const float* RC = (const float*)(ws + WS_ROPE); const float* RS = RC + 2048 * 16;
;     float* ML = (float*)((unsigned char*)p.out + OUT_ML);
;     LAS unsigned char* KA = lds + AT_KA; LAS unsigned char* VB = lds + AT_VB;
;     const float QSCALE = 0.08838834764831845f * 1.4426950408889634f;
;     u32x4 kr[8], vr[8];
;     int it = blockIdx.x;
;     if (it < 1536) { const AttnItem a0 = attn_item(it); attn_load(R1, a0, tid, kr, vr); }
.LBB0_570:
	s_mov_b32 s99, 0
	s_cmp_lt_i32 s90, 6
	s_cselect_b64 s[0:1], -1, 0
	s_and_b64 s[96:97], s[0:1], s[2:3]
	s_andn2_b64 vcc, exec, s[96:97]
	s_cbranch_vccnz .LBB0_629
	v_readfirstlane_b32 s100, v212
	s_nop 3
	s_cmp_ge_u32 s100, 0x100
	s_cbranch_scc0 .Lprio5_done
	s_setprio 1
.Lprio5_done:
	s_movk_i32 s98, 0x64
	s_cmp_lg_u32 s82, 0x100
	s_cbranch_scc1 .Lhm_nofuse
	s_mov_b32 s98, 0
	s_mov_b32 s99, 1
	v_readlane_b32 s100, v254, 23
	v_readlane_b32 s101, v254, 24
	v_lshlrev_b32_e32 v250, 4, v212
	v_mov_b32_e32 v251, s84
	v_lshl_add_u32 v250, v251, 15, v250
	v_lshlrev_b32_e32 v251, 11, v251
	v_and_b32_e32 v252, 0x1e0, v212
	v_add_u32_e32 v251, v251, v252
	v_and_b32_e32 v252, 7, v212
	v_lshl_add_u32 v251, v252, 2, v251
	v_add_u32_e32 v251, 0xfd80000, v251

; __device__ __forceinline__ unsigned xb_ld(unsigned* p)              { return __hip_atomic_load(p, __ATOMIC_RELAXED, __HIP_MEMORY_SCOPE_AGENT); }
; __device__ __forceinline__ void xcd_barrier_complete(unsigned* bar, unsigned x, unsigned& nloc, unsigned& nx) {
;     const unsigned G = gridDim.x * gridDim.y * gridDim.z;
;     unsigned sum, cnt, mine, sp = 0u;
;     for (;;) {
;         sum = 0u; cnt = 0u; mine = 0u;
; #pragma unroll
;         for (unsigned j = 0; j < 16; ++j) { const unsigned c = xb_ld(&bar[XB_XCNT(j)]); sum += c; cnt += (c > 0u) ? 1u : 0u; mine = (j == x) ? c : mine; }
; __device__ __forceinline__ void xcd_barrier(const XcdBarrier& b) {
;     asm volatile("s_waitcnt vmcnt(0)" ::: "memory");
;     __syncthreads();
;     if (threadIdx.x == 0) {
;         unsigned* bar = b.bar;
;         __builtin_amdgcn_s_waitcnt(0);
;         unsigned nloc = b.st[0], nx = b.st[1];
;         if (nloc == 0u) { xcd_barrier_complete(bar, b.x, nloc, nx); b.st[0] = nloc; b.st[1] = nx; }
.LBB0_629:
	s_setprio 0
	s_cmp_gt_i32 s91, 6
	s_cselect_b64 s[0:1], -1, 0
	s_and_b64 s[2:3], s[96:97], s[0:1]
	s_andn2_b64 vcc, exec, s[2:3]
	s_cbranch_vccnz .LBB0_679
	s_waitcnt vmcnt(0)
	s_waitcnt vmcnt(0) lgkmcnt(0)
	s_barrier
	s_mov_b64 s[2:3], exec
	v_readlane_b32 s4, v254, 1
	v_readlane_b32 s5, v254, 2
	s_and_b64 s[4:5], s[2:3], s[4:5]
	s_mov_b64 exec, s[4:5]
	s_cbranch_execz .LBB0_678
	v_readlane_b32 s4, v254, 22
	s_waitcnt vmcnt(0) expcnt(0) lgkmcnt(0)
	s_nop 0
	v_mov_b32_e32 v0, s4
	ds_read_b32 v2, v0
	ds_read_b32 v0, v0 offset:4
	s_waitcnt lgkmcnt(1)
	v_cmp_ne_u32_e32 vcc, 0, v2
	s_cbranch_vccnz .LBB0_646
	v_readlane_b32 s4, v254, 0
	s_mul_i32 s33, s83, s4
	s_add_u32 s4, s88, 0xffc0200
	s_addc_u32 s5, s89, 0
	s_add_u32 s6, s88, 0xffc0400
	s_addc_u32 s7, s89, 0
	s_add_u32 s8, s88, 0xffc0500
	s_addc_u32 s9, s89, 0
	s_add_u32 s10, s88, 0xffc0600
	s_addc_u32 s11, s89, 0
	s_add_u32 s12, s88, 0xffc0700
	s_addc_u32 s13, s89, 0
	s_add_u32 s14, s88, 0xffc0800
	s_addc_u32 s15, s89, 0
	s_add_u32 s16, s88, 0xffc0900
	s_addc_u32 s17, s89, 0
	s_add_u32 s18, s88, 0xffc0a00
	s_addc_u32 s19, s89, 0
	s_add_u32 s20, s88, 0xffc0b00
	s_addc_u32 s21, s89, 0
	s_add_u32 s22, s88, 0xffc0c00
	s_addc_u32 s23, s89, 0
	s_add_u32 s24, s88, 0xffc0d00
	s_addc_u32 s25, s89, 0
	s_add_u32 s26, s88, 0xffc0e00
	s_addc_u32 s27, s89, 0
	s_add_u32 s28, s88, 0xffc0f00
	s_addc_u32 s29, s89, 0
	s_add_u32 s30, s88, 0xffc1000
	s_addc_u32 s31, s89, 0
	s_add_u32 s34, s88, 0xffc1100
	s_addc_u32 s35, s89, 0
	s_add_u32 s36, s88, 0xffc1200
	s_addc_u32 s37, s89, 0
	s_add_u32 s38, s88, 0xffc1300
	s_mul_i32 s33, s33, s82
	s_addc_u32 s39, s89, 0
	s_mov_b32 s46, 1
	v_mov_b32_e32 v16, 0
	s_branch .LBB0_634
